# combine phase: group-output loads issued together with the LSE loads (one memory round trip per iteration instead of two), on top of A DMA restructure
# speedup vs baseline: 1.0009x; 1.0009x over previous
; DI unsigned pk2(float lo, float hi) { f32x2 v = {lo, hi}; bf16x2_t b = __builtin_convertvector(v, bf16x2_t); return __builtin_bit_cast(unsigned, b); }
; DI float bflo(unsigned u) { return __uint_as_float(u << 16); }
; DI float bfhi(unsigned u) { return __uint_as_float(u & 0xffff0000u); }
; DI int otid() { int t = threadIdx.x; asm volatile("" : "+v"(t)); return t; }
; DI void phase_combine(const Params& p) {
;   const bf16_t* G0 = (const bf16_t*)(p.ws + OFF_H); const bf16_t* G1 = G0 + (size_t)S * 512; bf16_t* OB = (bf16_t*)(p.ws + OFF_OB);
;   const float* LSE = (const float*)(p.ws + OFF_LSE);
;   for (int e = blockIdx.x * 512 + otid(); e < S * 64; e += gridDim.x * 512) {
;     const int tkn = e >> 6, c = e & 63, head = c >> 3;
;     const float l0 = LSE[((size_t)0 * S + tkn) * 8 + head], l1 = LSE[((size_t)1 * S + tkn) * 8 + head], l2 = LSE[((size_t)2 * S + tkn) * 8 + head];
;     const float mm = fmaxf(l0, fmaxf(l1, l2));
;     float w0 = __expf(l0 - mm), w1 = __expf(l1 - mm), w2 = __expf(l2 - mm);
;     const float iw = 1.0f / (w0 + w1 + w2); w0 *= iw; w1 *= iw; w2 *= iw;
;     const size_t off = (size_t)tkn * 512 + c * 8;
;     const u32x4 a = *(const u32x4*)(G0 + off), b = *(const u32x4*)(G1 + off), d = *(const u32x4*)(OB + off);
;     u32x4 o;
; #pragma unroll
;     for (int q = 0; q < 4; ++q) o[q] = pk2(w0 * bflo(a[q]) + w1 * bflo(b[q]) + w2 * bflo(d[q]), w0 * bfhi(a[q]) + w1 * bfhi(b[q]) + w2 * bfhi(d[q]));
;     *(u32x4*)(OB + off) = o;
;   }
.LBB0_654:
	v_ashrrev_i32_e32 v4, 6, v1
	v_ashrrev_i32_e32 v5, 31, v4
	v_lshlrev_b64 v[2:3], 5, v[4:5]
	v_lshl_add_u64 v[2:3], s[8:9], 0, v[2:3]
	v_lshl_add_u64 v[2:3], v[2:3], 0, v[172:173]
	v_add_co_u32_e32 v26, vcc, 0x80000, v2
	global_load_dword v28, v[2:3], off
	s_nop 0
	v_addc_co_u32_e32 v27, vcc, 0, v3, vcc
	global_load_dword v26, v[26:27], off
	v_add_co_u32_e32 v2, vcc, s12, v2
	v_lshlrev_b64 v[12:13], 10, v[4:5]
	s_nop 0
	v_addc_co_u32_e32 v3, vcc, 0, v3, vcc
	global_load_dword v2, v[2:3], off
	v_lshl_or_b32 v12, v0, 1, v12
	v_lshl_add_u64 v[4:5], s[20:21], 0, v[12:13]
	v_lshl_add_u64 v[20:21], s[74:75], 0, v[12:13]
	v_lshl_add_u64 v[8:9], s[10:11], 0, v[12:13]
	v_add_u32_e32 v1, s84, v1
	global_load_dwordx4 v[4:7], v[4:5], off
	global_load_dwordx4 v[8:11], v[8:9], off
	global_load_dwordx4 v[12:15], v[20:21], off
	s_waitcnt vmcnt(3)
	v_max3_f32 v3, v28, v26, v2
	v_sub_f32_e32 v27, v28, v3
	v_sub_f32_e32 v26, v26, v3
	v_mul_f32_e32 v27, 0x3fb8aa3b, v27
	v_mul_f32_e32 v26, 0x3fb8aa3b, v26
	v_sub_f32_e32 v2, v2, v3
	v_exp_f32_e32 v17, v27
	v_exp_f32_e32 v16, v26
	v_mul_f32_e32 v2, 0x3fb8aa3b, v2
	v_exp_f32_e32 v2, v2
	v_add_f32_e32 v3, v17, v16
	v_add_f32_e32 v3, v2, v3
	v_div_scale_f32 v26, s[6:7], v3, v3, 1.0
	v_rcp_f32_e32 v27, v26
	s_mov_b32 s6, 0xfffff
	v_fma_f32 v28, -v26, v27, 1.0
	v_fmac_f32_e32 v27, v28, v27
	v_div_scale_f32 v28, vcc, 1.0, v3, 1.0
	v_mul_f32_e32 v29, v28, v27
	v_fma_f32 v30, -v26, v29, v28
	v_fmac_f32_e32 v29, v30, v27
	v_fma_f32 v26, -v26, v29, v28
	v_div_fmas_f32 v26, v26, v27, v29
	v_div_fixup_f32 v18, v26, v3, 1.0
	v_pk_mul_f32 v[16:17], v[16:17], v[18:19] op_sel_hi:[1,0]
	v_mul_f32_e32 v2, v2, v18
	v_cmp_lt_i32_e32 vcc, s6, v1
	s_or_b64 s[4:5], vcc, s[4:5]
	s_waitcnt vmcnt(2)
	v_lshlrev_b32_e32 v22, 16, v4
	v_and_b32_e32 v19, 0xffff0000, v4
	s_waitcnt vmcnt(1)
	v_and_b32_e32 v23, 0xffff0000, v8
	v_lshlrev_b32_e32 v18, 16, v8
	v_pk_mul_f32 v[22:23], v[16:17], v[22:23] op_sel:[1,0] op_sel_hi:[0,1]
	s_waitcnt vmcnt(0)
	v_lshlrev_b32_e32 v24, 16, v12
	v_and_b32_e32 v25, 0xffff0000, v12
	v_pk_fma_f32 v[18:19], v[16:17], v[18:19], v[22:23]
	v_lshlrev_b32_e32 v8, 16, v5
	v_pk_fma_f32 v[18:19], v[2:3], v[24:25], v[18:19] op_sel_hi:[0,1,1]
	v_cvt_pk_bf16_f32 v4, v18, v19
	v_lshlrev_b32_e32 v18, 16, v9
	v_and_b32_e32 v9, 0xffff0000, v9
	v_and_b32_e32 v19, 0xffff0000, v5
	v_pk_mul_f32 v[8:9], v[16:17], v[8:9] op_sel:[1,0] op_sel_hi:[0,1]
	v_lshlrev_b32_e32 v12, 16, v13
	v_and_b32_e32 v13, 0xffff0000, v13
	v_pk_fma_f32 v[8:9], v[16:17], v[18:19], v[8:9]
	v_lshlrev_b32_e32 v18, 16, v14
	v_pk_fma_f32 v[8:9], v[2:3], v[12:13], v[8:9] op_sel_hi:[0,1,1]
	v_lshlrev_b32_e32 v12, 16, v6
	v_and_b32_e32 v13, 0xffff0000, v10
	v_cvt_pk_bf16_f32 v5, v8, v9
	v_lshlrev_b32_e32 v8, 16, v10
	v_and_b32_e32 v9, 0xffff0000, v6
	v_pk_mul_f32 v[12:13], v[16:17], v[12:13] op_sel:[1,0] op_sel_hi:[0,1]
	v_and_b32_e32 v19, 0xffff0000, v14
	v_pk_fma_f32 v[8:9], v[16:17], v[8:9], v[12:13]
	v_lshlrev_b32_e32 v10, 16, v7
	v_pk_fma_f32 v[8:9], v[2:3], v[18:19], v[8:9] op_sel_hi:[0,1,1]
	v_cvt_pk_bf16_f32 v6, v8, v9
	v_lshlrev_b32_e32 v8, 16, v11
	v_and_b32_e32 v11, 0xffff0000, v11
	v_and_b32_e32 v9, 0xffff0000, v7
	v_pk_mul_f32 v[10:11], v[16:17], v[10:11] op_sel:[1,0] op_sel_hi:[0,1]
	v_pk_fma_f32 v[8:9], v[16:17], v[8:9], v[10:11]
	v_lshlrev_b32_e32 v10, 16, v15
	v_and_b32_e32 v11, 0xffff0000, v15
	v_pk_fma_f32 v[2:3], v[2:3], v[10:11], v[8:9] op_sel_hi:[0,1,1]
	v_cvt_pk_bf16_f32 v7, v2, v3
	global_store_dwordx4 v[20:21], v[4:7], off
	s_andn2_b64 exec, exec, s[4:5]
	s_cbranch_execnz .LBB0_654
